# stack12 + grid seams: non-last XCD leaders poll the monotonic arrival counter (TOP) instead of the separate generation word -> one device-scope round trip less per seam
# baseline (speedup 1.0000x reference)
.LBB0_116:
	s_or_b64 exec, exec, s[10:11]
	v_cvt_f32_u32_e32 v5, v2
	s_waitcnt vmcnt(0)
	v_readfirstlane_b32 s0, v4
	s_add_u32 s10, s76, 0x3500
	s_addc_u32 s11, s77, 0
	s_add_u32 s98, s76, 0x3400
	s_addc_u32 s99, s77, 0
	v_rcp_iflag_f32_e32 v5, v5
	v_add_u32_e32 v3, s0, v3
	v_add_u32_e32 v6, 1, v3
	s_mov_b64 s[12:13], -1
	v_mul_f32_e32 v4, 0x4f7ffffe, v5
	v_cvt_u32_f32_e32 v4, v4
	v_sub_u32_e32 v5, 0, v2
	v_mul_lo_u32 v5, v5, v4
	v_mul_hi_u32 v5, v4, v5
	v_add_u32_e32 v4, v4, v5
	v_mul_hi_u32 v4, v3, v4
	v_mul_lo_u32 v5, v4, v2
	v_sub_u32_e32 v3, v3, v5
	v_add_u32_e32 v7, 1, v4
	v_cmp_ge_u32_e32 vcc, v3, v2
	v_sub_u32_e32 v5, v3, v2
	s_nop 0
	v_cndmask_b32_e32 v4, v4, v7, vcc
	v_cndmask_b32_e32 v3, v3, v5, vcc
	v_add_u32_e32 v5, 1, v4
	v_cmp_ge_u32_e32 vcc, v3, v2
	s_nop 1
	v_cndmask_b32_e32 v4, v4, v5, vcc
	v_mul_lo_u32 v3, v2, v4
	v_add_u32_e32 v2, v3, v2
	v_mov_b32_e32 v248, v2
	v_cmp_ne_u32_e32 vcc, v6, v2
	v_mov_b64_e32 v[2:3], s[10:11]
	s_and_saveexec_b64 s[8:9], vcc
	s_cbranch_execz .LBB0_128
	v_mov_b32_e32 v2, 0
	global_load_dword v3, v2, s[98:99] sc1
	s_mov_b64 s[16:17], 0
	s_waitcnt vmcnt(0)
	v_cmp_lt_u32_e32 vcc, v3, v248
	s_and_saveexec_b64 s[14:15], vcc
	s_cbranch_execz .LBB0_127
	s_add_u32 s12, s76, 0x200
	s_addc_u32 s13, s77, 0
	s_mov_b32 s0, 1
	s_branch .LBB0_120

.LBB0_122:
	global_load_dword v3, v2, s[98:99] sc1
	s_add_i32 s0, s0, 1
	s_mov_b64 s[20:21], -1
	s_waitcnt vmcnt(0)
	v_cmp_ge_u32_e32 vcc, v3, v248
	s_orn2_b64 s[24:25], vcc, exec
	s_branch .LBB0_119

.LBB0_869:
	s_or_b64 exec, exec, s[12:13]
	v_cvt_f32_u32_e32 v5, v2
	s_waitcnt vmcnt(0)
	v_readfirstlane_b32 s0, v4
	s_add_u32 s12, s76, 0x3500
	s_addc_u32 s13, s77, 0
	s_add_u32 s98, s76, 0x3400
	s_addc_u32 s99, s77, 0
	v_rcp_iflag_f32_e32 v5, v5
	v_add_u32_e32 v3, s0, v3
	v_add_u32_e32 v6, 1, v3
	s_mov_b64 s[14:15], -1
	v_mul_f32_e32 v4, 0x4f7ffffe, v5
	v_cvt_u32_f32_e32 v4, v4
	v_sub_u32_e32 v5, 0, v2
	v_mul_lo_u32 v5, v5, v4
	v_mul_hi_u32 v5, v4, v5
	v_add_u32_e32 v4, v4, v5
	v_mul_hi_u32 v4, v3, v4
	v_mul_lo_u32 v5, v4, v2
	v_sub_u32_e32 v3, v3, v5
	v_add_u32_e32 v7, 1, v4
	v_cmp_ge_u32_e32 vcc, v3, v2
	v_sub_u32_e32 v5, v3, v2
	s_nop 0
	v_cndmask_b32_e32 v4, v4, v7, vcc
	v_cndmask_b32_e32 v3, v3, v5, vcc
	v_add_u32_e32 v5, 1, v4
	v_cmp_ge_u32_e32 vcc, v3, v2
	s_nop 1
	v_cndmask_b32_e32 v4, v4, v5, vcc
	v_mul_lo_u32 v3, v2, v4
	v_add_u32_e32 v2, v3, v2
	v_mov_b32_e32 v248, v2
	v_cmp_ne_u32_e32 vcc, v6, v2
	v_mov_b64_e32 v[2:3], s[12:13]
	s_and_saveexec_b64 s[10:11], vcc
	s_cbranch_execz .LBB0_881
	v_mov_b32_e32 v2, 0
	global_load_dword v3, v2, s[98:99] sc1
	s_mov_b64 s[18:19], 0
	s_waitcnt vmcnt(0)
	v_cmp_lt_u32_e32 vcc, v3, v248
	s_and_saveexec_b64 s[16:17], vcc
	s_cbranch_execz .LBB0_880
	s_add_u32 s14, s76, 0x200
	s_addc_u32 s15, s77, 0
	s_mov_b32 s0, 1
	s_branch .LBB0_873

.LBB0_875:
	global_load_dword v3, v2, s[98:99] sc1
	s_add_i32 s0, s0, 1
	s_mov_b64 s[22:23], -1
	s_waitcnt vmcnt(0)
	v_cmp_ge_u32_e32 vcc, v3, v248
	s_orn2_b64 s[26:27], vcc, exec
	s_branch .LBB0_872

	.amdhsa_kernel _Z14nsa_hybrid_fwd4Args
		.amdhsa_group_segment_fixed_size 0
		.amdhsa_private_segment_fixed_size 0
		.amdhsa_kernarg_size 416
		.amdhsa_user_sgpr_count 2
		.amdhsa_user_sgpr_dispatch_ptr 0
		.amdhsa_user_sgpr_queue_ptr 0
		.amdhsa_user_sgpr_kernarg_segment_ptr 1
		.amdhsa_user_sgpr_dispatch_id 0
		.amdhsa_user_sgpr_kernarg_preload_length 0
		.amdhsa_user_sgpr_kernarg_preload_offset 0
		.amdhsa_user_sgpr_private_segment_size 0
		.amdhsa_uses_dynamic_stack 0
		.amdhsa_enable_private_segment 0
		.amdhsa_system_sgpr_workgroup_id_x 1
		.amdhsa_system_sgpr_workgroup_id_y 0
		.amdhsa_system_sgpr_workgroup_id_z 0
		.amdhsa_system_sgpr_workgroup_info 0
		.amdhsa_system_vgpr_workitem_id 0
		.amdhsa_next_free_vgpr 256
		.amdhsa_next_free_sgpr 102
		.amdhsa_accum_offset 256
		.amdhsa_reserve_vcc 1
		.amdhsa_float_round_mode_32 0
		.amdhsa_float_round_mode_16_64 0
		.amdhsa_float_denorm_mode_32 3
		.amdhsa_float_denorm_mode_16_64 3
		.amdhsa_dx10_clamp 1
		.amdhsa_ieee_mode 1
		.amdhsa_fp16_overflow 0
		.amdhsa_tg_split 0
		.amdhsa_exception_fp_ieee_invalid_op 0
		.amdhsa_exception_fp_denorm_src 0
		.amdhsa_exception_fp_ieee_div_zero 0
		.amdhsa_exception_fp_ieee_overflow 0
		.amdhsa_exception_fp_ieee_underflow 0
		.amdhsa_exception_fp_ieee_inexact 0
		.amdhsa_exception_int_div_zero 0
	.end_amdhsa_kernel

amdhsa.kernels:
  - .agpr_count:     0
    .args:
      - .offset:         0
        .size:           160
        .value_kind:     by_value
      - .offset:         160
        .size:           4
        .value_kind:     hidden_block_count_x
      - .offset:         164
        .size:           4
        .value_kind:     hidden_block_count_y
      - .offset:         168
        .size:           4
        .value_kind:     hidden_block_count_z
      - .offset:         172
        .size:           2
        .value_kind:     hidden_group_size_x
      - .offset:         174
        .size:           2
        .value_kind:     hidden_group_size_y
      - .offset:         176
        .size:           2
        .value_kind:     hidden_group_size_z
      - .offset:         178
        .size:           2
        .value_kind:     hidden_remainder_x
      - .offset:         180
        .size:           2
        .value_kind:     hidden_remainder_y
      - .offset:         182
        .size:           2
        .value_kind:     hidden_remainder_z
      - .offset:         200
        .size:           8
        .value_kind:     hidden_global_offset_x
      - .offset:         208
        .size:           8
        .value_kind:     hidden_global_offset_y
      - .offset:         216
        .size:           8
        .value_kind:     hidden_global_offset_z
      - .offset:         224
        .size:           2
        .value_kind:     hidden_grid_dims
      - .offset:         280
        .size:           4
        .value_kind:     hidden_dynamic_lds_size
    .group_segment_fixed_size: 0
    .kernarg_segment_align: 8
    .kernarg_segment_size: 416
    .language:       OpenCL C
    .language_version:
      - 2
      - 0
    .max_flat_workgroup_size: 512
    .name:           _Z14nsa_hybrid_fwd4Args
    .private_segment_fixed_size: 0
    .sgpr_count:     108
    .sgpr_spill_count: 58
    .symbol:         _Z14nsa_hybrid_fwd4Args.kd
    .uniform_work_group_size: 1
    .uses_dynamic_stack: false
    .vgpr_count:     256
    .vgpr_spill_count: 0
    .wavefront_size: 64
